# np7 with the ffn_w_in bf16 conversion moved from the LN1 phase into the w_out GEMM phase (half the workgroups before, half after their tile)
# speedup vs baseline: 1.0012x; 1.0012x over previous
.LBB0_1238:
	s_cmp_lt_i32 s68, 11
	s_cselect_b64 s[6:7], -1, 0
	s_and_b64 s[24:25], s[6:7], s[4:5]
	s_andn2_b64 vcc, exec, s[24:25]
	s_cbranch_vccnz .LBB0_1293
	s_cmpk_lg_u32 s70, 0x100
	s_cbranch_scc1 .Lp10_tiles
	s_bitcmp1_b32 s2, 3
	s_cbranch_scc1 .Lp10_tiles
.Lp10_conv:
	s_load_dwordx2 s[8:9], s[0:1], 0xd0
	v_lshlrev_b32_e32 v2, 2, v1
	v_lshlrev_b32_e32 v6, 5, v1
	v_lshrrev_b32_e32 v10, 6, v1
	v_and_b32_e32 v2, 0xfc, v2
	v_lshrrev_b32_e32 v11, 1, v1
	v_and_b32_e32 v6, 32, v6
	v_lshl_add_u32 v4, v2, 2, 0
	v_mul_u32_u24_e32 v5, 0x404, v10
	v_lshl_add_u32 v7, v11, 2, 0
	v_mul_u32_u24_e32 v8, 0x404, v6
	s_cmpk_gt_i32 s2, 0x15f
	v_mov_b32_e32 v3, 0
	v_add_u32_e32 v12, v4, v5
	v_add_u32_e32 v13, v7, v8
	v_lshlrev_b32_e32 v4, 2, v2
	v_lshlrev_b32_e32 v2, 1, v6
	s_waitcnt vmcnt(0) lgkmcnt(0)
	s_barrier
	s_cbranch_scc1 .Lp10_cvdone
	s_add_u32 s4, s66, 0xdc00000
	v_mov_b32_e32 v5, v3
	s_addc_u32 s5, s67, 0
	v_lshl_add_u64 v[6:7], s[8:9], 0, v[4:5]
	s_lshl_b32 s14, s2, 8
	s_lshl_b32 s15, s70, 8
	s_movk_i32 s16, 0x5800
	v_add_u32_e32 v5, 0x2020, v12
	v_add_u32_e32 v8, 0x2028, v12
	v_add_u32_e32 v9, 0x4040, v12
	v_add_u32_e32 v14, 0x4048, v12
	v_add_u32_e32 v15, 0x6060, v12
	v_add_u32_e32 v16, 0x6068, v12
	v_add_u32_e32 v17, 0x8080, v12
	v_add_u32_e32 v18, 0x8088, v12
	v_add_u32_e32 v19, 0xa0a0, v12
	v_add_u32_e32 v20, 0xa0a8, v12
	v_add_u32_e32 v21, 0xc0c0, v12
	v_add_u32_e32 v22, 0xc0c8, v12
	v_add_u32_e32 v23, 0xe0e0, v12
	v_add_u32_e32 v24, 0xe0e8, v12
	s_mov_b32 s17, s2

.Lp10_cvdone:
	s_bitcmp1_b32 s2, 3
	s_cbranch_scc1 .LBB0_1293
.Lp10_tiles:
	v_cmp_gt_u32_e32 vcc, 0x100, v1
	s_cbranch_vccz .Lgprio_11
	s_setprio 1

.LBB0_1292:
	s_waitcnt vmcnt(0)
	v_readlane_b32 s0, v240, 22
	v_readlane_b32 s1, v240, 23
	s_barrier
	s_cmpk_lg_u32 s70, 0x100
	s_cbranch_scc1 .LBB0_1293
	s_bitcmp1_b32 s2, 3
	s_cbranch_scc0 .LBB0_1293
	s_setprio 0
	s_branch .Lp10_conv

.LBB0_1361:
	s_cmp_lt_i32 s68, 12
	s_cselect_b64 s[6:7], -1, 0
	s_and_b64 s[12:13], s[6:7], s[4:5]
	s_andn2_b64 vcc, exec, s[12:13]
	v_lshrrev_b32_e32 v206, 4, v1
	s_cbranch_vccnz .LBB0_1371
	s_load_dwordx8 s[4:11], s[0:1], 0xc0
	v_and_b32_e32 v2, 60, v206
	v_lshl_add_u32 v18, s2, 5, v2
	s_movk_i32 s14, 0x4000
	v_cmp_gt_i32_e32 vcc, s14, v18
	s_and_saveexec_b64 s[14:15], vcc
	s_cbranch_execz .LBB0_1365
	v_mbcnt_lo_u32_b32 v3, -1, 0
	v_mbcnt_hi_u32_b32 v3, -1, v3
	v_and_b32_e32 v7, 64, v3
	v_add_u32_e32 v7, 64, v7
	v_xor_b32_e32 v8, 32, v3
	v_cmp_lt_i32_e32 vcc, v8, v7
	v_lshlrev_b32_e32 v2, 3, v1
	v_and_b32_e32 v2, 0x1f8, v2
	v_cndmask_b32_e32 v8, v3, v8, vcc
	v_lshlrev_b32_e32 v71, 2, v8
	v_xor_b32_e32 v8, 16, v3
	v_cmp_lt_i32_e32 vcc, v8, v7
	v_mov_b32_e32 v21, 0
	v_lshlrev_b32_e32 v20, 1, v2
	v_cndmask_b32_e32 v8, v3, v8, vcc
	v_lshlrev_b32_e32 v72, 2, v8
	v_xor_b32_e32 v8, 8, v3
	v_cmp_lt_i32_e32 vcc, v8, v7
	v_lshl_add_u64 v[4:5], s[66:67], 0, v[20:21]
	s_lshl_b32 s19, s70, 5
	v_cndmask_b32_e32 v8, v3, v8, vcc
	v_lshlrev_b32_e32 v73, 2, v8
	v_xor_b32_e32 v8, 4, v3
	v_cmp_lt_i32_e32 vcc, v8, v7
	v_lshlrev_b32_e32 v20, 2, v2
	s_waitcnt lgkmcnt(0)
	v_lshl_add_u64 v[24:25], s[4:5], 0, v[20:21]
	v_cndmask_b32_e32 v8, v3, v8, vcc
	v_lshlrev_b32_e32 v74, 2, v8
	v_xor_b32_e32 v8, 2, v3
	v_cmp_lt_i32_e32 vcc, v8, v7
	v_lshl_add_u64 v[26:27], s[6:7], 0, v[20:21]
	s_add_u32 s6, s66, 0x1a00000
	v_cndmask_b32_e32 v8, v3, v8, vcc
	v_lshlrev_b32_e32 v75, 2, v8
	v_xor_b32_e32 v8, 1, v3
	v_cmp_lt_i32_e32 vcc, v8, v7
	s_mov_b64 s[4:5], 0x9c00000
	s_mov_b64 s[16:17], 0x5c00000
	v_or_b32_e32 v6, 0x200, v2
	s_addc_u32 s7, s67, 0
	v_cndmask_b32_e32 v3, v3, v8, vcc
	v_lshl_add_u64 v[28:29], v[4:5], 0, s[4:5]
	s_mov_b64 s[4:5], 0x1c00000
	s_mov_b32 s22, 0x3727c5ac
	v_lshl_add_u64 v[22:23], v[4:5], 0, s[16:17]
	v_lshlrev_b32_e32 v76, 2, v3
	v_lshl_add_u64 v[30:31], v[4:5], 0, s[4:5]
	s_mov_b64 s[4:5], 0
	s_movk_i32 s20, 0x1fff
	s_movk_i32 s21, 0x6000
	v_mov_b64_e32 v[32:33], s[6:7]
	s_mov_b64 s[6:7], 0x4000
	s_mov_b64 s[16:17], 0x3000
	v_lshlrev_b32_e32 v20, 2, v2
	s_mov_b32 s18, 0x3a800000
	v_lshlrev_b32_e32 v34, 2, v6
	v_mov_b32_e32 v35, v21
	v_mov_b64_e32 v[36:37], s[22:23]
	s_mov_b32 s22, 0x800000
	s_movk_i32 s23, 0x3fff
	global_load_dwordx4 v[130:133], v[24:25], off
	global_load_dwordx4 v[134:137], v[24:25], off offset:16
	global_load_dwordx4 v[138:141], v[24:25], off offset:2048
	global_load_dwordx4 v[142:145], v[24:25], off offset:2064
	global_load_dwordx4 v[146:149], v[26:27], off
	global_load_dwordx4 v[150:153], v[26:27], off offset:16
	global_load_dwordx4 v[154:157], v[26:27], off offset:2048
	global_load_dwordx4 v[158:161], v[26:27], off offset:2064
	s_waitcnt vmcnt(0)

.LBB0_1365:
	s_or_b64 exec, exec, s[14:15]
	s_cmpk_eq_i32 s70, 0x100
	s_cbranch_scc1 .LBB0_1371
	v_lshlrev_b32_e32 v2, 2, v1
	v_lshlrev_b32_e32 v6, 5, v1
	v_lshrrev_b32_e32 v10, 6, v1
	v_and_b32_e32 v2, 0xfc, v2
	v_lshrrev_b32_e32 v11, 1, v1
	v_and_b32_e32 v6, 32, v6
	v_lshl_add_u32 v4, v2, 2, 0
	v_mul_u32_u24_e32 v5, 0x404, v10
	v_lshl_add_u32 v7, v11, 2, 0
	v_mul_u32_u24_e32 v8, 0x404, v6
	s_cmpk_gt_i32 s2, 0x15f
	v_mov_b32_e32 v3, 0
	v_add_u32_e32 v12, v4, v5
	v_add_u32_e32 v13, v7, v8
	v_lshlrev_b32_e32 v4, 2, v2
	v_lshlrev_b32_e32 v2, 1, v6
	s_waitcnt vmcnt(0) lgkmcnt(0)
	s_barrier
	s_cbranch_scc1 .LBB0_1368
	s_add_u32 s4, s66, 0xdc00000
	v_mov_b32_e32 v5, v3
	s_addc_u32 s5, s67, 0
	v_lshl_add_u64 v[6:7], s[8:9], 0, v[4:5]
	s_lshl_b32 s14, s2, 8
	s_lshl_b32 s15, s70, 8
	s_movk_i32 s16, 0x5800
	v_add_u32_e32 v5, 0x2020, v12
	v_add_u32_e32 v8, 0x2028, v12
	v_add_u32_e32 v9, 0x4040, v12
	v_add_u32_e32 v14, 0x4048, v12
	v_add_u32_e32 v15, 0x6060, v12
	v_add_u32_e32 v16, 0x6068, v12
	v_add_u32_e32 v17, 0x8080, v12
	v_add_u32_e32 v18, 0x8088, v12
	v_add_u32_e32 v19, 0xa0a0, v12
	v_add_u32_e32 v20, 0xa0a8, v12
	v_add_u32_e32 v21, 0xc0c0, v12
	v_add_u32_e32 v22, 0xc0c8, v12
	v_add_u32_e32 v23, 0xe0e0, v12
	v_add_u32_e32 v24, 0xe0e8, v12
	s_mov_b32 s17, s2
